# v68 + conv_wT load hoist + attention taken-branch targets (second-buffer QK / PV code) aligned to 64 bytes
# speedup vs baseline: 1.0018x; 1.0018x over previous
.LBB0_216:
	s_and_b32 s50, s28, 1
	s_cmp_gt_i32 s47, s45
	s_cbranch_scc1 .LBB0_228
	v_mov_b32_e32 v233, v183
	s_lshl_b32 s28, s50, 15
	s_add_i32 s51, s28, 0
	v_ashrrev_i32_e32 v234, 5, v233
	v_lshlrev_b32_e32 v237, 2, v233
	v_bfe_u32 v231, v233, 2, 2
	s_setprio 1
	s_cmp_eq_u32 s50, 0
	s_cbranch_scc1 .Lattn_qk_b0
	ds_read_b128 v[64:67], v209 offset:32768
	ds_read_b128 v[68:71], v210 offset:32768
	ds_read_b128 v[72:75], v211 offset:32768
	ds_read_b128 v[76:79], v212 offset:32768
	ds_read_b128 v[112:115], v209 offset:40960
	ds_read_b128 v[116:119], v210 offset:40960
	ds_read_b128 v[120:123], v211 offset:40960
	ds_read_b128 v[124:127], v212 offset:40960
	s_waitcnt lgkmcnt(7)
	v_mfma_f32_32x32x16_bf16 v[96:111], v[64:67], v[130:133], 0
	s_waitcnt lgkmcnt(6)
	v_mfma_f32_32x32x16_bf16 v[96:111], v[68:71], v[134:137], v[96:111]
	s_waitcnt lgkmcnt(5)
	v_mfma_f32_32x32x16_bf16 v[96:111], v[72:75], v[138:141], v[96:111]
	s_waitcnt lgkmcnt(4)
	v_mfma_f32_32x32x16_bf16 v[96:111], v[76:79], v[142:145], v[96:111]
	s_waitcnt lgkmcnt(3)
	v_mfma_f32_32x32x16_bf16 v[80:95], v[112:115], v[130:133], 0
	s_waitcnt lgkmcnt(2)
	v_mfma_f32_32x32x16_bf16 v[80:95], v[116:119], v[134:137], v[80:95]
	s_waitcnt lgkmcnt(1)
	v_mfma_f32_32x32x16_bf16 v[80:95], v[120:123], v[138:141], v[80:95]
	s_waitcnt lgkmcnt(0)
	v_mfma_f32_32x32x16_bf16 v[80:95], v[124:127], v[142:145], v[80:95]
	s_branch .Lattn_qk_join
	.p2align 6

.LBB0_227:
	s_waitcnt lgkmcnt(0)
	v_add_f32_e32 v81, v81, v82
	v_fmac_f32_e32 v81, v232, v80
	s_setprio 1
	s_cmp_eq_u32 s50, 0
	s_cbranch_scc1 .Lattn_pv_b0
	ds_read_b64_tr_b16 v[92:93], v213 offset:49152
	ds_read_b64_tr_b16 v[94:95], v214 offset:49152
	ds_read_b64_tr_b16 v[96:97], v215 offset:49152
	ds_read_b64_tr_b16 v[98:99], v216 offset:49152
	ds_read_b64_tr_b16 v[100:101], v217 offset:49152
	ds_read_b64_tr_b16 v[102:103], v218 offset:49152
	ds_read_b64_tr_b16 v[104:105], v219 offset:49152
	ds_read_b64_tr_b16 v[106:107], v220 offset:49152
	ds_read_b64_tr_b16 v[108:109], v213 offset:53248
	ds_read_b64_tr_b16 v[110:111], v214 offset:53248
	ds_read_b64_tr_b16 v[112:113], v215 offset:53248
	ds_read_b64_tr_b16 v[114:115], v216 offset:53248
	v_cvt_pk_bf16_f32 v82, v246, v247
	v_cvt_pk_bf16_f32 v83, v248, v249
	v_cvt_pk_bf16_f32 v84, v250, v251
	v_cvt_pk_bf16_f32 v85, v252, v253
	s_nop 1
	s_waitcnt lgkmcnt(10)
	v_mfma_f32_32x32x16_bf16 v[48:63], v[92:95], v[82:85], v[48:63]
	v_cvt_pk_bf16_f32 v86, v238, v239
	v_cvt_pk_bf16_f32 v87, v240, v241
	v_cvt_pk_bf16_f32 v88, v242, v243
	v_cvt_pk_bf16_f32 v89, v244, v245
	ds_read_b64_tr_b16 v[116:117], v217 offset:53248
	ds_read_b64_tr_b16 v[118:119], v218 offset:53248
	s_waitcnt lgkmcnt(10)
	v_mfma_f32_32x32x16_bf16 v[32:47], v[96:99], v[82:85], v[32:47]
	ds_read_b64_tr_b16 v[120:121], v219 offset:53248
	ds_read_b64_tr_b16 v[122:123], v220 offset:53248
	s_waitcnt lgkmcnt(10)
	v_mfma_f32_32x32x16_bf16 v[16:31], v[100:103], v[82:85], v[16:31]
	ds_read_b64_tr_b16 v[92:93], v213 offset:57344
	ds_read_b64_tr_b16 v[94:95], v214 offset:57344
	s_waitcnt lgkmcnt(10)
	v_mfma_f32_32x32x16_bf16 v[0:15], v[104:107], v[82:85], v[0:15]
	ds_read_b64_tr_b16 v[96:97], v215 offset:57344
	ds_read_b64_tr_b16 v[98:99], v216 offset:57344
	s_waitcnt lgkmcnt(10)
	v_mfma_f32_32x32x16_bf16 v[48:63], v[108:111], v[86:89], v[48:63]
	v_cvt_pk_bf16_f32 v82, v64, v65
	v_cvt_pk_bf16_f32 v83, v66, v67
	v_cvt_pk_bf16_f32 v84, v68, v69
	v_cvt_pk_bf16_f32 v85, v70, v71
	ds_read_b64_tr_b16 v[100:101], v217 offset:57344
	ds_read_b64_tr_b16 v[102:103], v218 offset:57344
	s_waitcnt lgkmcnt(10)
	v_mfma_f32_32x32x16_bf16 v[32:47], v[112:115], v[86:89], v[32:47]
	ds_read_b64_tr_b16 v[104:105], v219 offset:57344
	ds_read_b64_tr_b16 v[106:107], v220 offset:57344
	s_waitcnt lgkmcnt(10)
	v_mfma_f32_32x32x16_bf16 v[16:31], v[116:119], v[86:89], v[16:31]
	ds_read_b64_tr_b16 v[108:109], v213 offset:61440
	ds_read_b64_tr_b16 v[110:111], v214 offset:61440
	s_waitcnt lgkmcnt(10)
	v_mfma_f32_32x32x16_bf16 v[0:15], v[120:123], v[86:89], v[0:15]
	ds_read_b64_tr_b16 v[112:113], v215 offset:61440
	ds_read_b64_tr_b16 v[114:115], v216 offset:61440
	s_waitcnt lgkmcnt(10)
	v_mfma_f32_32x32x16_bf16 v[48:63], v[92:95], v[82:85], v[48:63]
	v_cvt_pk_bf16_f32 v86, v72, v73
	v_cvt_pk_bf16_f32 v87, v74, v75
	v_cvt_pk_bf16_f32 v88, v76, v77
	v_cvt_pk_bf16_f32 v89, v78, v79
	ds_read_b64_tr_b16 v[116:117], v217 offset:61440
	ds_read_b64_tr_b16 v[118:119], v218 offset:61440
	s_waitcnt lgkmcnt(10)
	v_mfma_f32_32x32x16_bf16 v[32:47], v[96:99], v[82:85], v[32:47]
	ds_read_b64_tr_b16 v[120:121], v219 offset:61440
	ds_read_b64_tr_b16 v[122:123], v220 offset:61440
	s_waitcnt lgkmcnt(10)
	v_mfma_f32_32x32x16_bf16 v[16:31], v[100:103], v[82:85], v[16:31]
	s_waitcnt lgkmcnt(8)
	v_mfma_f32_32x32x16_bf16 v[0:15], v[104:107], v[82:85], v[0:15]
	s_waitcnt lgkmcnt(6)
	v_mfma_f32_32x32x16_bf16 v[48:63], v[108:111], v[86:89], v[48:63]
	s_waitcnt lgkmcnt(4)
	v_mfma_f32_32x32x16_bf16 v[32:47], v[112:115], v[86:89], v[32:47]
	s_waitcnt lgkmcnt(2)
	v_mfma_f32_32x32x16_bf16 v[16:31], v[116:119], v[86:89], v[16:31]
	s_waitcnt lgkmcnt(0)
	v_mfma_f32_32x32x16_bf16 v[0:15], v[120:123], v[86:89], v[0:15]
	s_branch .Lattn_pv_join
	.p2align 6
